# rowwise phase: x-hi and y loads issued with x-lo, store-drain wait skipped, forget-bias load hoisted out of row loop; static prio for waves 4-7 in attention; GEMM epilogue L1 prefetch; MLA gate loads
# speedup vs baseline: 1.0286x; 1.0219x over previous
.LBB0_371:
	v_readlane_b32 s6, v254, 57
	v_readlane_b32 s7, v254, 58
	s_and_b64 vcc, exec, s[6:7]
	s_cbranch_vccz .LBB0_403
	global_load_dwordx4 v[30:33], v[30:31], off offset:2064
	v_ashrrev_i32_e32 v37, 6, v34
	v_readlane_b32 s6, v253, 44
	v_or_b32_e32 v84, 0x204, v36
	v_or_b32_e32 v86, 0x200, v36
	v_or_b32_e32 v88, 4, v36
	s_mov_b32 s23, s87
	v_and_b32_e32 v36, 32, v34
	v_add_u32_e32 v37, s6, v37
	s_lshl_b64 s[16:17], s[22:23], 4
	s_lshl_b32 s86, s66, 4
	v_cmp_eq_u32_e64 s[6:7], 0, v36
	v_and_b32_e32 v36, 16, v34
	s_cmp_gt_u32 s66, 1
	v_cmp_eq_u32_e64 s[8:9], 0, v36
	v_and_b32_e32 v36, 8, v34
	v_and_b32_e32 v34, 7, v34
	s_cselect_b64 s[26:27], -1, 0
	v_cmp_eq_u32_e64 s[12:13], 0, v34
	v_lshrrev_b32_e32 v34, 3, v35
	s_lshl_b32 s14, s66, 2
	v_readlane_b32 s18, v254, 56
	v_and_or_b32 v34, s14, 8, v34
	v_readlane_b32 s14, v253, 47
	v_mul_lo_u32 v82, s18, v37
	v_cmp_eq_u32_e64 s[10:11], 0, v36
	v_lshlrev_b32_e32 v36, 10, v35
	v_mov_b32_e32 v37, v1
	v_readlane_b32 s15, v253, 48
	v_readlane_b32 s44, v253, 24
	v_readlane_b32 s56, v253, 36
	v_lshl_add_u64 v[90:91], s[14:15], 0, v[36:37]
	v_lshlrev_b32_e32 v36, 2, v34
	v_readlane_b32 s57, v253, 37
	v_ashrrev_i32_e32 v83, 31, v82
	v_readlane_b32 s14, v254, 61
	v_lshl_add_u64 v[92:93], s[56:57], 0, v[36:37]
	global_load_dword v196, v[92:93], off
	v_lshlrev_b64 v[36:37], 11, v[82:83]
	v_lshl_or_b32 v36, v35, 4, v36
	v_readlane_b32 s15, v254, 62
	v_readlane_b32 s46, v253, 26
	v_readlane_b32 s47, v253, 27
	v_lshl_add_u64 v[94:95], s[14:15], 0, v[36:37]
	v_lshlrev_b64 v[36:37], 12, v[82:83]
	v_readlane_b32 s14, v254, 63
	v_lshl_or_b32 v36, v35, 5, v36
	v_readlane_b32 s15, v255, 0
	v_mov_b32_e32 v98, v1
	v_mov_b32_e32 v99, v1
	v_mov_b32_e32 v64, 0
	v_mov_b32_e32 v83, s18
	v_readlane_b32 s18, v253, 45
	v_lshl_add_u32 v85, v35, 4, 0
	v_lshl_add_u64 v[96:97], s[14:15], 0, v[36:37]
	v_mov_b32_e32 v87, -1
	s_mov_b64 s[38:39], 0
	v_mov_b64_e32 v[108:109], v[98:99]
	v_mov_b64_e32 v[102:103], v[98:99]
	v_mov_b64_e32 v[100:101], v[98:99]
	v_mov_b64_e32 v[106:107], v[98:99]
	v_mov_b64_e32 v[104:105], v[98:99]
	v_mov_b64_e32 v[112:113], v[98:99]
	v_mov_b64_e32 v[110:111], v[98:99]
	v_mov_b32_e32 v65, v64
	v_mov_b32_e32 v36, v64
	v_mov_b32_e32 v37, v64
	v_mov_b32_e32 v62, v64
	v_mov_b32_e32 v63, v64
	v_mov_b32_e32 v34, v64
	v_mov_b32_e32 v35, v64
	v_mov_b32_e32 v60, v64
	v_mov_b32_e32 v61, v64
	v_mov_b32_e32 v40, v64
	v_mov_b32_e32 v41, v64
	v_mov_b32_e32 v58, v64
	v_mov_b32_e32 v59, v64
	v_mov_b32_e32 v38, v64
	v_mov_b32_e32 v39, v64
	v_mov_b32_e32 v42, v64
	v_mov_b32_e32 v43, v64
	v_mov_b32_e32 v44, v64
	v_mov_b32_e32 v45, v64
	v_mov_b32_e32 v46, v64
	v_mov_b32_e32 v47, v64
	v_mov_b32_e32 v48, v64
	v_mov_b32_e32 v49, v64
	v_mov_b32_e32 v56, v64
	v_mov_b32_e32 v57, v64
	v_mov_b32_e32 v54, v64
	v_mov_b32_e32 v55, v64
	v_mov_b32_e32 v52, v64
	v_mov_b32_e32 v53, v64
	v_mov_b32_e32 v50, v64
	v_mov_b32_e32 v51, v64
	v_readlane_b32 s19, v253, 46
	s_movk_i32 s36, 0x3000
	s_mov_b64 s[46:47], 0x1000
	v_readlane_b32 s45, v253, 25
	v_readlane_b32 s48, v253, 28
	v_readlane_b32 s49, v253, 29
	v_readlane_b32 s50, v253, 30
	v_readlane_b32 s51, v253, 31
	v_readlane_b32 s52, v253, 32
	v_readlane_b32 s53, v253, 33
	v_readlane_b32 s54, v253, 34
	v_readlane_b32 s55, v253, 35
	v_readlane_b32 s58, v253, 38
	v_readlane_b32 s59, v253, 39
	s_branch .LBB0_376

.LBB0_376:
	s_mov_b32 s14, 0x8000
	s_mov_b32 s100, 0
	v_cmp_gt_i32_e32 vcc, s14, v82
	s_or_b64 s[40:41], s[40:41], exec
	s_and_saveexec_b64 s[44:45], vcc
	s_cbranch_execz .LBB0_375
	v_ashrrev_i32_e32 v114, 11, v82
	v_cmp_ne_u32_e32 vcc, v114, v87
	s_and_saveexec_b64 s[14:15], vcc
	s_cbranch_execz .LBB0_387
	v_ashrrev_i32_e32 v115, 31, v114
	v_lshl_add_u64 v[50:51], s[16:17], 0, v[114:115]
	v_mov_b64_e32 v[52:53], s[18:19]
	v_mad_u64_u32 v[52:53], s[22:23], v50, s36, v[52:53]
	v_mad_i32_i24 v53, v51, s36, v53
	s_mov_b64 s[22:23], 0x2000
	s_and_b64 vcc, exec, s[4:5]
	v_lshl_add_u64 v[78:79], v[52:53], 0, s[22:23]
	s_cbranch_vccnz .LBB0_380
	v_lshl_add_u64 v[42:43], v[78:79], 0, v[0:1]
	global_load_dwordx4 v[42:45], v[42:43], off

.LBB0_387:
	s_or_b64 exec, exec, s[14:15]
	s_mov_b64 s[14:15], -1
	s_and_b64 vcc, exec, s[26:27]
	s_cbranch_vccz .LBB0_389
	s_waitcnt lgkmcnt(0)
	global_load_dwordx4 v[66:69], v[94:95], off offset:-1024
	global_load_dwordx4 v[182:185], v[94:95], off
	v_add_co_u32_e32 v186, vcc, 0xe7d7b000, v94
	s_nop 1
	v_addc_co_u32_e32 v187, vcc, -1, v95, vcc
	global_load_dwordx4 v[188:191], v[186:187], off
	global_load_dwordx4 v[192:195], v[186:187], off offset:-1024
	s_mov_b32 s100, 1
	s_waitcnt vmcnt(0)
	v_lshlrev_b32_e32 v74, 16, v66
	v_and_b32_e32 v75, 0xffff0000, v66
	v_lshlrev_b32_e32 v76, 16, v67
	v_and_b32_e32 v77, 0xffff0000, v67
	v_lshlrev_b32_e32 v78, 16, v68
	v_and_b32_e32 v79, 0xffff0000, v68
	v_lshlrev_b32_e32 v80, 16, v69
	v_and_b32_e32 v81, 0xffff0000, v69
	s_cbranch_execnz .LBB0_391
	s_branch .LBB0_390

.LBB0_391:
	s_andn2_b64 vcc, exec, s[26:27]
	s_mov_b64 s[14:15], -1
	s_cbranch_vccnz .LBB0_400
	v_mov_b32_e32 v70, v182
	v_mov_b32_e32 v71, v183
	v_mov_b32_e32 v72, v184
	v_mov_b32_e32 v73, v185
	s_waitcnt vmcnt(0)
	v_lshlrev_b32_e32 v66, 16, v70
	s_waitcnt lgkmcnt(0)
	v_and_b32_e32 v67, 0xffff0000, v70
	v_lshlrev_b32_e32 v68, 16, v71
	v_and_b32_e32 v69, 0xffff0000, v71
	v_lshlrev_b32_e32 v70, 16, v72
	v_and_b32_e32 v71, 0xffff0000, v72
	v_lshlrev_b32_e32 v72, 16, v73
	v_and_b32_e32 v73, 0xffff0000, v73
	s_cbranch_execz .LBB0_401

.LBB0_394:
	s_cmp_eq_u32 s100, 1
	s_cbranch_scc0 .Lrow_yslow
	s_waitcnt vmcnt(0)
	v_mov_b32_e32 v116, v188
	v_mov_b32_e32 v117, v189
	v_mov_b32_e32 v118, v190
	v_mov_b32_e32 v119, v191
	v_mov_b32_e32 v120, v192
	v_mov_b32_e32 v121, v193
	v_mov_b32_e32 v122, v194
	v_mov_b32_e32 v123, v195
	s_branch .Lrow_yjoin

.Lrow_yjoin:
	v_lshlrev_b32_e32 v124, 16, v116
	s_waitcnt vmcnt(0)
	v_lshlrev_b32_e32 v128, 16, v120
	v_and_b32_e32 v129, 0xffff0000, v120
	v_lshlrev_b32_e32 v120, 16, v121
	v_and_b32_e32 v121, 0xffff0000, v121
	v_lshlrev_b32_e32 v130, 16, v122
	v_and_b32_e32 v131, 0xffff0000, v122
	v_pk_mul_f32 v[140:141], v[128:129], v[128:129]
	v_pk_mul_f32 v[142:143], v[120:121], v[120:121]
	v_lshlrev_b32_e32 v122, 16, v123
	v_and_b32_e32 v123, 0xffff0000, v123
	v_pk_mul_f32 v[144:145], v[130:131], v[130:131]
	v_add_f32_e32 v115, v142, v143
	v_add_f32_e32 v140, v140, v141
	v_and_b32_e32 v125, 0xffff0000, v116
	v_pk_mul_f32 v[146:147], v[122:123], v[122:123]
	v_add_f32_e32 v141, v144, v145
	v_add_f32_e32 v115, v140, v115
	v_lshlrev_b32_e32 v116, 16, v117
	v_and_b32_e32 v117, 0xffff0000, v117
	v_pk_mul_f32 v[138:139], v[124:125], v[124:125]
	v_add_f32_e32 v89, v146, v147
	v_add_f32_e32 v115, v141, v115
	v_lshlrev_b32_e32 v126, 16, v118
	v_and_b32_e32 v127, 0xffff0000, v118
	v_pk_mul_f32 v[136:137], v[116:117], v[116:117]
	v_add_f32_e32 v138, v138, v139
	v_add_f32_e32 v89, v89, v115
	v_lshlrev_b32_e32 v118, 16, v119
	v_and_b32_e32 v119, 0xffff0000, v119
	v_pk_mul_f32 v[134:135], v[126:127], v[126:127]
	v_add_f32_e32 v136, v136, v137
	v_add_f32_e32 v89, v138, v89
	v_pk_mul_f32 v[132:133], v[118:119], v[118:119]
	v_add_f32_e32 v134, v134, v135
	v_add_f32_e32 v89, v136, v89
	v_add_f32_e32 v132, v132, v133
	v_add_f32_e32 v89, v134, v89
	v_add_f32_e32 v89, v132, v89
	s_nop 1
	v_add_f32_dpp v89, v89, v89 quad_perm:[1,0,3,2] row_mask:0xf bank_mask:0xf bound_ctrl:1
	s_nop 1
	v_add_f32_dpp v89, v89, v89 quad_perm:[2,3,0,1] row_mask:0xf bank_mask:0xf bound_ctrl:1
	s_nop 1
	v_add_f32_dpp v89, v89, v89 row_half_mirror row_mask:0xf bank_mask:0xf bound_ctrl:1
	s_nop 1
	v_add_f32_dpp v89, v89, v89 row_mirror row_mask:0xf bank_mask:0xf bound_ctrl:1
	v_mov_b32_e32 v115, v89
	s_nop 1
	v_permlane16_swap_b32_e32 v89, v115
	v_add_f32_e32 v89, v89, v115
	v_mov_b32_e32 v115, v89
	s_nop 1
	v_permlane32_swap_b32_e32 v89, v115
	v_add_f32_e32 v89, v89, v115
	v_fmamk_f32 v89, v89, 0x3a800000, v245
	v_mul_f32_e32 v115, 0x4b800000, v89
	v_cmp_gt_f32_e32 vcc, s75, v89
	s_nop 1
	v_cndmask_b32_e32 v89, v89, v115, vcc
	v_rsq_f32_e32 v89, v89
	s_nop 0
	v_mul_f32_e32 v115, 0x45800000, v89
	v_cndmask_b32_e32 v132, v89, v115, vcc
	v_pk_mul_f32 v[128:129], v[132:133], v[128:129] op_sel_hi:[0,1]
	v_pk_mul_f32 v[120:121], v[132:133], v[120:121] op_sel_hi:[0,1]
	v_pk_mul_f32 v[130:131], v[132:133], v[130:131] op_sel_hi:[0,1]
	v_pk_mul_f32 v[122:123], v[132:133], v[122:123] op_sel_hi:[0,1]
	v_pk_mul_f32 v[124:125], v[132:133], v[124:125] op_sel_hi:[0,1]
	v_pk_mul_f32 v[116:117], v[132:133], v[116:117] op_sel_hi:[0,1]
	v_pk_mul_f32 v[126:127], v[132:133], v[126:127] op_sel_hi:[0,1]
	v_pk_mul_f32 v[118:119], v[132:133], v[118:119] op_sel_hi:[0,1]
	v_pk_mul_f32 v[128:129], v[6:7], v[128:129]
	v_pk_mul_f32 v[120:121], v[8:9], v[120:121]
	v_pk_mul_f32 v[130:131], v[2:3], v[130:131]
	v_pk_mul_f32 v[122:123], v[4:5], v[122:123]
	v_pk_mul_f32 v[124:125], v[22:23], v[124:125]
	v_pk_mul_f32 v[116:117], v[24:25], v[116:117]
	v_pk_mul_f32 v[126:127], v[18:19], v[126:127]
	v_pk_mul_f32 v[118:119], v[20:21], v[118:119]
	v_pk_fma_f32 v[74:75], v[42:43], v[128:129], v[74:75]
	v_pk_fma_f32 v[76:77], v[44:45], v[120:121], v[76:77]
	v_pk_fma_f32 v[78:79], v[46:47], v[130:131], v[78:79]
	v_pk_fma_f32 v[80:81], v[48:49], v[122:123], v[80:81]
	s_waitcnt lgkmcnt(0)
	v_pk_fma_f32 v[66:67], v[38:39], v[124:125], v[66:67]
	v_pk_fma_f32 v[68:69], v[40:41], v[116:117], v[68:69]
	v_pk_fma_f32 v[70:71], v[34:35], v[126:127], v[70:71]
	v_pk_fma_f32 v[72:73], v[36:37], v[118:119], v[72:73]
	v_cvt_pk_bf16_f32 v116, v74, v75
	v_cvt_pk_bf16_f32 v117, v76, v77
	v_cvt_pk_bf16_f32 v118, v78, v79
	v_cvt_pk_bf16_f32 v119, v80, v81
	v_cvt_pk_bf16_f32 v120, v66, v67
	v_cvt_pk_bf16_f32 v121, v68, v69
	v_cvt_pk_bf16_f32 v122, v70, v71
	v_cvt_pk_bf16_f32 v123, v72, v73
	global_store_dwordx4 v[94:95], v[116:119], off offset:-1024
	global_store_dwordx4 v[94:95], v[120:123], off
	s_branch .Lrow_nowait

.Lrow_nowait:
	v_pk_mul_f32 v[130:131], v[74:75], v[74:75]
	v_pk_mul_f32 v[128:129], v[76:77], v[76:77]
	v_add_f32_e32 v89, v131, v130
	v_add_f32_e32 v89, v128, v89
	v_pk_mul_f32 v[126:127], v[78:79], v[78:79]
	v_add_f32_e32 v89, v129, v89
	v_add_f32_e32 v89, v126, v89
	v_pk_mul_f32 v[124:125], v[80:81], v[80:81]
	v_add_f32_e32 v89, v127, v89
	v_add_f32_e32 v89, v124, v89
	s_waitcnt lgkmcnt(0)
	v_pk_mul_f32 v[116:117], v[66:67], v[66:67]
	v_add_f32_e32 v89, v125, v89
	v_add_f32_e32 v89, v116, v89
	v_pk_mul_f32 v[118:119], v[68:69], v[68:69]
	v_add_f32_e32 v89, v117, v89
	v_add_f32_e32 v89, v118, v89
	v_pk_mul_f32 v[120:121], v[70:71], v[70:71]
	v_add_f32_e32 v89, v119, v89
	v_add_f32_e32 v89, v120, v89
	v_pk_mul_f32 v[122:123], v[72:73], v[72:73]
	v_add_f32_e32 v89, v121, v89
	v_add_f32_e32 v89, v122, v89
	v_add_f32_e32 v89, v123, v89
	s_nop 1
	v_add_f32_dpp v89, v89, v89 quad_perm:[1,0,3,2] row_mask:0xf bank_mask:0xf bound_ctrl:1
	s_nop 1
	v_add_f32_dpp v89, v89, v89 quad_perm:[2,3,0,1] row_mask:0xf bank_mask:0xf bound_ctrl:1
	s_nop 1
	v_add_f32_dpp v89, v89, v89 row_half_mirror row_mask:0xf bank_mask:0xf bound_ctrl:1
	s_nop 1
	v_add_f32_dpp v89, v89, v89 row_mirror row_mask:0xf bank_mask:0xf bound_ctrl:1
	v_mov_b32_e32 v115, v89
	s_nop 1
	v_permlane16_swap_b32_e32 v89, v115
	v_add_f32_e32 v89, v89, v115
	v_mov_b32_e32 v115, v89
	s_nop 1
	v_permlane32_swap_b32_e32 v89, v115
	v_add_f32_e32 v89, v89, v115
	v_fmamk_f32 v89, v89, 0x3a800000, v245
	v_mul_f32_e32 v115, 0x4b800000, v89
	v_cmp_gt_f32_e32 vcc, s75, v89
	s_nop 1
	v_cndmask_b32_e32 v89, v89, v115, vcc
	v_rsq_f32_e32 v89, v89
	s_nop 0
	v_mul_f32_e32 v115, 0x45800000, v89
	v_cndmask_b32_e32 v118, v89, v115, vcc
	v_pk_mul_f32 v[74:75], v[74:75], v[118:119] op_sel_hi:[1,0]
	s_nop 0
	v_pk_mul_f32 v[74:75], v[10:11], v[74:75]
	s_nop 0
	v_pk_fma_f32 v[124:125], v[110:111], v[74:75], v[50:51]
	v_pk_mul_f32 v[74:75], v[76:77], v[118:119] op_sel_hi:[1,0]
	s_nop 0
	v_pk_mul_f32 v[74:75], v[12:13], v[74:75]
	s_nop 0
	v_pk_fma_f32 v[122:123], v[112:113], v[74:75], v[52:53]
	v_pk_mul_f32 v[74:75], v[78:79], v[118:119] op_sel_hi:[1,0]
	v_add_co_u32_e32 v78, vcc, 0xe7d7b000, v94
	v_pk_mul_f32 v[74:75], v[14:15], v[74:75]
	s_nop 0
	v_addc_co_u32_e32 v79, vcc, -1, v95, vcc
	v_pk_fma_f32 v[120:121], v[104:105], v[74:75], v[54:55]
	v_pk_mul_f32 v[74:75], v[80:81], v[118:119] op_sel_hi:[1,0]
	v_cvt_pk_bf16_f32 v76, v120, v121
	v_pk_mul_f32 v[74:75], v[16:17], v[74:75]
	s_andn2_b64 vcc, exec, s[94:95]
	v_pk_fma_f32 v[116:117], v[106:107], v[74:75], v[56:57]
	v_cvt_pk_bf16_f32 v74, v124, v125
	v_cvt_pk_bf16_f32 v75, v122, v123
	v_cvt_pk_bf16_f32 v77, v116, v117
	global_store_dwordx4 v[78:79], v[74:77], off offset:-1024
	v_mov_b32_e32 v78, 0
	v_mov_b32_e32 v79, 0
	v_cndmask_b32_e64 v74, 0, 1, s[94:95]
	v_cmp_ne_u32_e64 s[14:15], 1, v74
	v_mov_b32_e32 v80, 0
	v_mov_b32_e32 v81, 0
	v_mov_b32_e32 v76, 0
	v_mov_b32_e32 v77, 0
	v_mov_b32_e32 v74, 0
	v_mov_b32_e32 v75, 0
	s_cbranch_vccnz .LBB0_397
	ds_read_b128 v[74:77], v85
	ds_read_b128 v[78:81], v85 offset:1024
	ds_read_b128 v[126:129], v85 offset:16384
	ds_read_b128 v[130:133], v85 offset:17408
	ds_read_b128 v[134:137], v85 offset:2048
	ds_read_b128 v[138:141], v85 offset:3072
	ds_read_b128 v[142:145], v85 offset:18432
	ds_read_b128 v[146:149], v85 offset:19456
	ds_read_b128 v[150:153], v85 offset:4096
	ds_read_b128 v[154:157], v85 offset:5120
	ds_read_b128 v[158:161], v85 offset:20480
	ds_read_b128 v[162:165], v85 offset:21504
	ds_read_b128 v[166:169], v85 offset:6144
	ds_read_b128 v[170:173], v85 offset:7168
	ds_read_b128 v[174:177], v85 offset:22528
	ds_read_b128 v[178:181], v85 offset:23552
	s_waitcnt lgkmcnt(14)
	v_pk_fma_f32 v[74:75], v[124:125], v[74:75], 0 op_sel_hi:[0,1,0]
	v_pk_fma_f32 v[74:75], v[124:125], v[78:79], v[74:75] op_sel:[1,0,0]
	s_waitcnt lgkmcnt(13)
	v_pk_fma_f32 v[78:79], v[124:125], v[126:127], 0 op_sel_hi:[0,1,0]
	s_waitcnt lgkmcnt(12)
	v_pk_fma_f32 v[78:79], v[124:125], v[130:131], v[78:79] op_sel:[1,0,0]
	v_pk_fma_f32 v[76:77], v[124:125], v[76:77], 0 op_sel_hi:[0,1,0]
	s_waitcnt lgkmcnt(9)
	v_pk_fma_f32 v[78:79], v[122:123], v[142:143], v[78:79] op_sel_hi:[0,1,1]
	s_waitcnt lgkmcnt(8)
	v_pk_fma_f32 v[78:79], v[122:123], v[146:147], v[78:79] op_sel:[1,0,0]
	v_pk_fma_f32 v[76:77], v[124:125], v[80:81], v[76:77] op_sel:[1,0,0]
	s_waitcnt lgkmcnt(5)
	v_pk_fma_f32 v[78:79], v[120:121], v[158:159], v[78:79] op_sel_hi:[0,1,1]
	s_waitcnt lgkmcnt(4)
	v_pk_fma_f32 v[78:79], v[120:121], v[162:163], v[78:79] op_sel:[1,0,0]
	v_pk_fma_f32 v[74:75], v[122:123], v[134:135], v[74:75] op_sel_hi:[0,1,1]
	s_waitcnt lgkmcnt(1)
	v_pk_fma_f32 v[78:79], v[116:117], v[174:175], v[78:79] op_sel_hi:[0,1,1]
	s_waitcnt lgkmcnt(0)
	v_pk_fma_f32 v[80:81], v[116:117], v[178:179], v[78:79] op_sel:[1,0,0]
	v_pk_fma_f32 v[78:79], v[124:125], v[128:129], 0 op_sel_hi:[0,1,0]
	v_pk_fma_f32 v[78:79], v[124:125], v[132:133], v[78:79] op_sel:[1,0,0]
	v_pk_fma_f32 v[76:77], v[122:123], v[136:137], v[76:77] op_sel_hi:[0,1,1]
	v_pk_fma_f32 v[78:79], v[122:123], v[144:145], v[78:79] op_sel_hi:[0,1,1]
	v_pk_fma_f32 v[74:75], v[122:123], v[138:139], v[74:75] op_sel:[1,0,0]
	v_pk_fma_f32 v[76:77], v[122:123], v[140:141], v[76:77] op_sel:[1,0,0]
	v_pk_fma_f32 v[78:79], v[122:123], v[148:149], v[78:79] op_sel:[1,0,0]
	v_pk_fma_f32 v[74:75], v[120:121], v[150:151], v[74:75] op_sel_hi:[0,1,1]
	v_pk_fma_f32 v[76:77], v[120:121], v[152:153], v[76:77] op_sel_hi:[0,1,1]
	v_pk_fma_f32 v[78:79], v[120:121], v[160:161], v[78:79] op_sel_hi:[0,1,1]
	v_pk_fma_f32 v[74:75], v[120:121], v[154:155], v[74:75] op_sel:[1,0,0]
	v_pk_fma_f32 v[76:77], v[120:121], v[156:157], v[76:77] op_sel:[1,0,0]
	v_pk_fma_f32 v[78:79], v[120:121], v[164:165], v[78:79] op_sel:[1,0,0]
	v_pk_fma_f32 v[74:75], v[116:117], v[166:167], v[74:75] op_sel_hi:[0,1,1]
	v_pk_fma_f32 v[76:77], v[116:117], v[168:169], v[76:77] op_sel_hi:[0,1,1]
	v_pk_fma_f32 v[78:79], v[116:117], v[176:177], v[78:79] op_sel_hi:[0,1,1]
	v_pk_fma_f32 v[74:75], v[116:117], v[170:171], v[74:75] op_sel:[1,0,0]
	v_pk_fma_f32 v[76:77], v[116:117], v[172:173], v[76:77] op_sel:[1,0,0]
	v_pk_fma_f32 v[78:79], v[116:117], v[180:181], v[78:79] op_sel:[1,0,0]
.LBB0_397:
	v_mov_b32_e32 v119, v118
	v_pk_mul_f32 v[66:67], v[66:67], v[118:119]
	s_nop 0
	v_pk_mul_f32 v[66:67], v[26:27], v[66:67]
	s_nop 0
	v_pk_fma_f32 v[120:121], v[100:101], v[66:67], v[58:59]
	v_pk_mul_f32 v[66:67], v[68:69], v[118:119]
	s_nop 0
	v_pk_mul_f32 v[66:67], v[28:29], v[66:67]
	s_nop 0
	v_pk_fma_f32 v[116:117], v[102:103], v[66:67], v[60:61]
	v_pk_mul_f32 v[66:67], v[70:71], v[118:119]
	v_cvt_pk_bf16_f32 v70, v120, v121
	v_pk_mul_f32 v[66:67], v[30:31], v[66:67]
	v_cvt_pk_bf16_f32 v71, v116, v117
	v_pk_fma_f32 v[68:69], v[108:109], v[66:67], v[62:63]
	v_pk_mul_f32 v[66:67], v[72:73], v[118:119]
	v_add_co_u32_e32 v118, vcc, 0xe7d7b000, v94
	v_pk_mul_f32 v[66:67], v[32:33], v[66:67]
	s_nop 0
	v_addc_co_u32_e32 v119, vcc, -1, v95, vcc
	v_pk_fma_f32 v[66:67], v[98:99], v[66:67], v[64:65]
	v_cvt_pk_bf16_f32 v72, v68, v69
	v_cvt_pk_bf16_f32 v73, v66, v67
	s_and_b64 vcc, exec, s[14:15]
	global_store_dwordx4 v[118:119], v[70:73], off
	s_cbranch_vccnz .LBB0_374
	ds_read_b128 v[70:73], v85 offset:8192
	ds_read_b128 v[122:125], v85 offset:24576
	s_waitcnt lgkmcnt(1)
	v_fmac_f32_e32 v74, v120, v70
	v_fmac_f32_e32 v75, v120, v71
	v_fmac_f32_e32 v76, v120, v72
	v_fmac_f32_e32 v77, v120, v73
	s_waitcnt lgkmcnt(0)
	v_fmac_f32_e32 v80, v120, v122
	v_fmac_f32_e32 v81, v120, v123
	v_fmac_f32_e32 v78, v120, v124
	v_fmac_f32_e32 v79, v120, v125
	ds_read_b128 v[70:73], v85 offset:9216
	ds_read_b128 v[122:125], v85 offset:25600
	s_waitcnt lgkmcnt(1)
	v_fmac_f32_e32 v74, v121, v70
	v_fmac_f32_e32 v75, v121, v71
	v_fmac_f32_e32 v76, v121, v72
	v_fmac_f32_e32 v77, v121, v73
	s_waitcnt lgkmcnt(0)
	v_fmac_f32_e32 v80, v121, v122
	v_fmac_f32_e32 v81, v121, v123
	v_fmac_f32_e32 v78, v121, v124
	v_fmac_f32_e32 v79, v121, v125
	ds_read_b128 v[70:73], v85 offset:10240
	ds_read_b128 v[118:121], v85 offset:26624
	s_waitcnt lgkmcnt(1)
	v_fmac_f32_e32 v74, v116, v70
	v_fmac_f32_e32 v75, v116, v71
	v_fmac_f32_e32 v76, v116, v72
	v_fmac_f32_e32 v77, v116, v73
	s_waitcnt lgkmcnt(0)
	v_fmac_f32_e32 v80, v116, v118
	v_fmac_f32_e32 v81, v116, v119
	v_fmac_f32_e32 v78, v116, v120
	v_fmac_f32_e32 v79, v116, v121
	ds_read_b128 v[70:73], v85 offset:11264
	ds_read_b128 v[118:121], v85 offset:27648
	s_waitcnt lgkmcnt(1)
	v_fmac_f32_e32 v74, v117, v70
	v_fmac_f32_e32 v75, v117, v71
	v_fmac_f32_e32 v76, v117, v72
	v_fmac_f32_e32 v77, v117, v73
	s_waitcnt lgkmcnt(0)
	v_fmac_f32_e32 v80, v117, v118
	v_fmac_f32_e32 v81, v117, v119
	v_fmac_f32_e32 v78, v117, v120
	v_fmac_f32_e32 v79, v117, v121
	ds_read_b128 v[70:73], v85 offset:12288
	ds_read_b128 v[116:119], v85 offset:28672
	s_waitcnt lgkmcnt(1)
	v_fmac_f32_e32 v74, v68, v70
	v_fmac_f32_e32 v75, v68, v71
	v_fmac_f32_e32 v76, v68, v72
	v_fmac_f32_e32 v77, v68, v73
	s_waitcnt lgkmcnt(0)
	v_fmac_f32_e32 v80, v68, v116
	v_fmac_f32_e32 v81, v68, v117
	v_fmac_f32_e32 v78, v68, v118
	v_fmac_f32_e32 v79, v68, v119
	ds_read_b128 v[70:73], v85 offset:13312
	ds_read_b128 v[116:119], v85 offset:29696
	s_waitcnt lgkmcnt(1)
	v_fmac_f32_e32 v74, v69, v70
	v_fmac_f32_e32 v75, v69, v71
	v_fmac_f32_e32 v76, v69, v72
	v_fmac_f32_e32 v77, v69, v73
	s_waitcnt lgkmcnt(0)
	v_fmac_f32_e32 v80, v69, v116
	v_fmac_f32_e32 v81, v69, v117
	v_fmac_f32_e32 v78, v69, v118
	v_fmac_f32_e32 v79, v69, v119
	ds_read_b128 v[68:71], v85 offset:14336
	ds_read_b128 v[116:119], v85 offset:30720
	s_waitcnt lgkmcnt(1)
	v_fmac_f32_e32 v74, v66, v68
	v_fmac_f32_e32 v75, v66, v69
	v_fmac_f32_e32 v76, v66, v70
	v_fmac_f32_e32 v77, v66, v71
	s_waitcnt lgkmcnt(0)
	v_fmac_f32_e32 v80, v66, v116
	v_fmac_f32_e32 v81, v66, v117
	v_fmac_f32_e32 v78, v66, v118
	v_fmac_f32_e32 v79, v66, v119
	ds_read_b128 v[68:71], v85 offset:15360
	ds_read_b128 v[116:119], v85 offset:31744
	v_xor_b32_e32 v66, 32, v250
	s_waitcnt lgkmcnt(1)
	v_fmac_f32_e32 v74, v67, v68
	v_fmac_f32_e32 v75, v67, v69
	v_fmac_f32_e32 v76, v67, v70
	v_fmac_f32_e32 v77, v67, v71
	s_waitcnt lgkmcnt(0)
	v_fmac_f32_e32 v80, v67, v116
	v_fmac_f32_e32 v81, v67, v117
	v_fmac_f32_e32 v78, v67, v118
	v_fmac_f32_e32 v79, v67, v119
	v_and_b32_e32 v67, 64, v250
	v_add_u32_e32 v67, 64, v67
	v_cmp_lt_i32_e32 vcc, v66, v67
	v_cndmask_b32_e64 v68, v74, v80, s[6:7]
	v_cndmask_b32_e64 v69, v80, v74, s[6:7]
	v_cndmask_b32_e32 v66, v250, v66, vcc
	v_lshlrev_b32_e32 v66, 2, v66
	ds_bpermute_b32 v68, v66, v68
	v_cndmask_b32_e64 v70, v81, v75, s[6:7]
	v_cndmask_b32_e64 v71, v78, v76, s[6:7]
	v_cndmask_b32_e64 v72, v79, v77, s[6:7]
	s_waitcnt lgkmcnt(0)
	v_add_f32_e32 v68, v69, v68
	v_cndmask_b32_e64 v69, v75, v81, s[6:7]
	ds_bpermute_b32 v69, v66, v69
	s_waitcnt lgkmcnt(0)
	v_add_f32_e32 v69, v70, v69
	v_cndmask_b32_e64 v70, v76, v78, s[6:7]
	ds_bpermute_b32 v70, v66, v70
	s_waitcnt lgkmcnt(0)
	v_add_f32_e32 v70, v71, v70
	v_cndmask_b32_e64 v71, v77, v79, s[6:7]
	ds_bpermute_b32 v66, v66, v71
	v_xor_b32_e32 v71, 16, v250
	v_cmp_lt_i32_e32 vcc, v71, v67
	s_waitcnt lgkmcnt(0)
	v_add_f32_e32 v66, v72, v66
	v_cndmask_b32_e32 v71, v250, v71, vcc
	v_lshlrev_b32_e32 v71, 2, v71
	v_cndmask_b32_e64 v72, v68, v70, s[8:9]
	v_cndmask_b32_e64 v68, v70, v68, s[8:9]
	ds_bpermute_b32 v70, v71, v72
	s_waitcnt lgkmcnt(0)
	v_add_f32_e32 v68, v68, v70
	v_cndmask_b32_e64 v70, v69, v66, s[8:9]
	v_cndmask_b32_e64 v66, v66, v69, s[8:9]
	ds_bpermute_b32 v69, v71, v70
	s_waitcnt lgkmcnt(0)
	v_add_f32_e32 v66, v66, v69
	v_cndmask_b32_e64 v69, v68, v66, s[10:11]
	v_cndmask_b32_e64 v66, v66, v68, s[10:11]
	v_xor_b32_e32 v68, 8, v250
	v_cmp_lt_i32_e32 vcc, v68, v67
	s_nop 1
	v_cndmask_b32_e32 v68, v250, v68, vcc
	v_lshlrev_b32_e32 v68, 2, v68
	ds_bpermute_b32 v68, v68, v69
	s_waitcnt lgkmcnt(0)
	v_add_f32_e32 v66, v66, v68
	v_xor_b32_e32 v68, 4, v250
	v_cmp_lt_i32_e32 vcc, v68, v67
	s_nop 1
	v_cndmask_b32_e32 v68, v250, v68, vcc
	v_lshlrev_b32_e32 v68, 2, v68
	ds_bpermute_b32 v68, v68, v66
	s_waitcnt lgkmcnt(0)
	v_add_f32_e32 v66, v66, v68
	v_xor_b32_e32 v68, 2, v250
	v_cmp_lt_i32_e32 vcc, v68, v67
	s_nop 1
	v_cndmask_b32_e32 v68, v250, v68, vcc
	v_lshlrev_b32_e32 v68, 2, v68
	ds_bpermute_b32 v68, v68, v66
	s_waitcnt lgkmcnt(0)
	v_add_f32_e32 v66, v66, v68
	v_xor_b32_e32 v68, 1, v250
	v_cmp_lt_i32_e32 vcc, v68, v67
	s_nop 1
	v_cndmask_b32_e32 v67, v250, v68, vcc
	v_lshlrev_b32_e32 v67, 2, v67
	ds_bpermute_b32 v67, v67, v66
	s_and_saveexec_b64 s[14:15], s[12:13]
	s_cbranch_execz .LBB0_373
	s_waitcnt lgkmcnt(0)
	v_add_f32_e32 v66, v66, v67
	v_mov_b32_e32 v67, v196
	s_mov_b32 s22, 0xbfb8aa3b
	v_ashrrev_i32_e32 v115, 31, v114
	v_and_b32_e32 v68, 0x7ff, v82
	v_lshlrev_b32_e32 v68, 2, v68
	v_mov_b32_e32 v69, v1
	s_nop 0
	v_add_f32_e32 v66, v66, v67
	v_min_f32_e32 v70, 0, v66
	v_mul_f32_e64 v66, |v66|, s22
	v_exp_f32_e32 v66, v66
	s_nop 0
	v_add_f32_e32 v66, 1.0, v66
	v_log_f32_e32 v66, v66
	s_nop 0
	v_fmac_f32_e32 v70, 0xbf317218, v66
	v_lshlrev_b64 v[66:67], 16, v[114:115]
	v_lshl_add_u64 v[66:67], v[90:91], 0, v[66:67]
	v_lshl_add_u64 v[66:67], v[66:67], 0, v[68:69]
	global_store_dword v[66:67], v70, off
	s_branch .LBB0_373

.LBB0_630:
	s_or_b64 exec, exec, s[4:5]
	s_and_b64 vcc, exec, s[94:95]
	v_readlane_b32 s94, v255, 24
	s_mov_b64 s[6:7], -1
	v_readlane_b32 s95, v255, 25
	s_waitcnt lgkmcnt(0)
	s_barrier
	v_readfirstlane_b32 s100, v244
	s_nop 0
	s_lshr_b32 s100, s100, 6
	s_cmp_lt_u32 s100, 4
	s_cbranch_scc1 .Lprio_0
	s_setprio 1
.Lprio_0:
	s_cbranch_vccz .LBB0_843
	v_cvt_f32_u32_e32 v0, s66
	v_readlane_b32 s44, v253, 24
	v_readlane_b32 s4, v255, 28
	v_readlane_b32 s56, v253, 36
	v_mul_f32_e32 v0, 0xbedd9914, v0
	v_exp_f32_e32 v0, v0
	v_readlane_b32 s57, v253, 37
	s_lshl_b32 s86, s4, 8
	v_readlane_b32 s58, v253, 38
	v_readlane_b32 s59, v253, 39
	s_mov_b64 s[16:17], s[56:57]
	s_lshl_b32 s64, s4, 7
	s_lshl_b64 s[6:7], s[86:87], 2
	s_mov_b64 s[18:19], s[58:59]
	v_mov_b32_e32 v2, 0x3f4ccccd
	v_readlane_b32 s46, v253, 26
	v_readlane_b32 s47, v253, 27
	v_readlane_b32 s50, v253, 30
	v_readlane_b32 s51, v253, 31
	s_add_u32 s8, s18, s6
	v_fmamk_f32 v152, v0, 0xbf19999a, v2
	v_readlane_b32 s46, v255, 16
	v_readlane_b32 s50, v255, 18
	s_addc_u32 s9, s19, s7
	v_readlane_b32 s18, v255, 22
	v_sub_f32_e32 v130, 1.0, v152
	s_mov_b32 s4, 0
	v_readlane_b32 s47, v255, 17
	v_readlane_b32 s51, v255, 19
	v_readlane_b32 s19, v255, 23
	v_mov_b32_e32 v131, v130
	s_mov_b32 s65, 0
	v_readlane_b32 s45, v253, 25
	v_readlane_b32 s48, v253, 28
	v_readlane_b32 s49, v253, 29
	v_readlane_b32 s52, v253, 32
	v_readlane_b32 s53, v253, 33
	v_readlane_b32 s54, v253, 34
	v_readlane_b32 s55, v253, 35
	s_branch .LBB0_633

.LBB0_677:
.LBB0_678:
	s_add_i32 s72, s55, 1
	s_cmp_ge_i32 s72, s58
	s_cselect_b64 s[48:49], -1, 0
	s_cmp_ge_i32 s55, s63
	s_waitcnt vmcnt(0)
	s_cselect_b64 s[84:85], -1, 0
	s_barrier
	s_or_b64 s[84:85], s[84:85], s[48:49]
	s_mov_b64 s[48:49], -1
	s_and_b64 vcc, exec, s[84:85]
	s_cbranch_vccz .LBB0_682
	s_nop 0
	s_cbranch_execz .LBB0_683

.LBB0_681:
	s_and_b32 s44, s55, 3
	s_mulk_i32 s44, 0x7400
	v_add_u32_e32 v0, s44, v159
	v_add_u32_e32 v0, 0x2400, v0
	ds_read_b64_tr_b16 v[160:161], v0 offset:0
	ds_read_b64_tr_b16 v[162:163], v0 offset:0xa00
	ds_read_b64_tr_b16 v[164:165], v0 offset:64
	ds_read_b64_tr_b16 v[166:167], v0 offset:0xa40
	ds_read_b64_tr_b16 v[168:169], v0 offset:0x80
	ds_read_b64_tr_b16 v[170:171], v0 offset:0xa80
	ds_read_b64_tr_b16 v[172:173], v0 offset:0xc0
	ds_read_b64_tr_b16 v[174:175], v0 offset:0xac0
	ds_read_b64_tr_b16 v[176:177], v0 offset:0x1400
	ds_read_b64_tr_b16 v[178:179], v0 offset:0x1e00
	ds_read_b64_tr_b16 v[180:181], v0 offset:0x1440
	ds_read_b64_tr_b16 v[182:183], v0 offset:0x1e40
	ds_read_b64_tr_b16 v[184:185], v0 offset:0x1480
	ds_read_b64_tr_b16 v[186:187], v0 offset:0x1e80
	ds_read_b64_tr_b16 v[188:189], v0 offset:0x14c0
	ds_read_b64_tr_b16 v[190:191], v0 offset:0x1ec0
	s_nop 0
	s_waitcnt lgkmcnt(8)
	s_nop 0
	v_mfma_f32_32x32x16_bf16 v[82:97], v[160:163], v[126:129], v[82:97]
	v_mfma_f32_32x32x16_bf16 v[34:49], v[164:167], v[126:129], v[34:49]
	v_mfma_f32_32x32x16_bf16 v[18:33], v[168:171], v[126:129], v[18:33]
	v_mfma_f32_32x32x16_bf16 v[2:17], v[172:175], v[126:129], v[2:17]
	ds_read_b64_tr_b16 v[126:127], v0 offset:0x2800
	ds_read_b64_tr_b16 v[128:129], v0 offset:0x3200
	ds_read_b64_tr_b16 v[160:161], v0 offset:0x2840
	ds_read_b64_tr_b16 v[162:163], v0 offset:0x3240
	ds_read_b64_tr_b16 v[164:165], v0 offset:0x2880
	ds_read_b64_tr_b16 v[166:167], v0 offset:0x3280
	ds_read_b64_tr_b16 v[168:169], v0 offset:0x28c0
	ds_read_b64_tr_b16 v[170:171], v0 offset:0x32c0
	s_waitcnt lgkmcnt(8)
	s_nop 0
	v_mfma_f32_32x32x16_bf16 v[82:97], v[176:179], v[122:125], v[82:97]
	v_mfma_f32_32x32x16_bf16 v[34:49], v[180:183], v[122:125], v[34:49]
	v_mfma_f32_32x32x16_bf16 v[18:33], v[184:187], v[122:125], v[18:33]
	v_mfma_f32_32x32x16_bf16 v[2:17], v[188:191], v[122:125], v[2:17]
	ds_read_b64_tr_b16 v[122:123], v0 offset:0x3c00
	ds_read_b64_tr_b16 v[124:125], v0 offset:0x4600
	ds_read_b64_tr_b16 v[172:173], v0 offset:0x3c40
	ds_read_b64_tr_b16 v[174:175], v0 offset:0x4640
	ds_read_b64_tr_b16 v[176:177], v0 offset:0x3c80
	ds_read_b64_tr_b16 v[178:179], v0 offset:0x4680
	ds_read_b64_tr_b16 v[180:181], v0 offset:0x3cc0
	ds_read_b64_tr_b16 v[182:183], v0 offset:0x46c0
	s_waitcnt lgkmcnt(8)
	s_nop 0
	v_mfma_f32_32x32x16_bf16 v[82:97], v[126:129], v[114:117], v[82:97]
	s_waitcnt lgkmcnt(0)
	v_mfma_f32_32x32x16_bf16 v[34:49], v[160:163], v[114:117], v[34:49]
	v_mfma_f32_32x32x16_bf16 v[18:33], v[164:167], v[114:117], v[18:33]
	v_mfma_f32_32x32x16_bf16 v[2:17], v[168:171], v[114:117], v[2:17]
	v_mfma_f32_32x32x16_bf16 v[82:97], v[122:125], v[118:121], v[82:97]
	v_mfma_f32_32x32x16_bf16 v[34:49], v[172:175], v[118:121], v[34:49]
	v_mfma_f32_32x32x16_bf16 v[18:33], v[176:179], v[118:121], v[18:33]
	v_mfma_f32_32x32x16_bf16 v[2:17], v[180:183], v[118:121], v[2:17]
	s_nop 0
	s_add_i32 s44, s55, 3
	s_cmp_ge_i32 s44, s58
	s_cbranch_scc1 .LBB0_672
	s_branch .LBB0_685

.LBB0_683:
	s_and_b32 s48, s72, 3
	s_mulk_i32 s48, 0x7400
	v_add_u32_e32 v0, s48, v153
	ds_read_b128 v[50:53], v0
	ds_read_b128 v[160:163], v0 offset:32
	ds_read_b128 v[164:167], v0 offset:64
	ds_read_b128 v[168:171], v0 offset:96
	ds_read_b128 v[66:69], v0 offset:4608
	ds_read_b128 v[172:175], v0 offset:4640
	ds_read_b128 v[176:179], v0 offset:4672
	ds_read_b128 v[180:183], v0 offset:4704
	s_nop 0
	s_waitcnt lgkmcnt(0)
	v_mfma_f32_32x32x16_bf16 v[50:65], v[50:53], v[98:101], 0
	v_mfma_f32_32x32x16_bf16 v[66:81], v[66:69], v[98:101], 0
	v_mfma_f32_32x32x16_bf16 v[50:65], v[160:163], v[102:105], v[50:65]
	v_mfma_f32_32x32x16_bf16 v[66:81], v[172:175], v[102:105], v[66:81]
	v_mfma_f32_32x32x16_bf16 v[50:65], v[164:167], v[106:109], v[50:65]
	v_mfma_f32_32x32x16_bf16 v[66:81], v[176:179], v[106:109], v[66:81]
	v_mfma_f32_32x32x16_bf16 v[50:65], v[168:171], v[110:113], v[50:65]
	v_mfma_f32_32x32x16_bf16 v[66:81], v[180:183], v[110:113], v[66:81]
	s_andn2_b64 vcc, exec, s[44:45]
	s_cbranch_vccz .LBB0_681
.LBB0_684:
	s_nop 0
	s_add_i32 s44, s55, 3
	s_cmp_ge_i32 s44, s58
	s_cbranch_scc1 .LBB0_672

.LBB0_694:
.LBB0_695:
	s_add_i32 s72, s71, 1
	s_cmp_ge_i32 s72, s58
	s_cselect_b64 s[48:49], -1, 0
	s_cmp_lt_i32 s72, s58
	s_cselect_b64 s[54:55], -1, 0
	s_cmp_lt_i32 s71, s63
	s_cselect_b64 s[84:85], -1, 0
	s_cmp_gt_i32 s71, -2
	s_waitcnt vmcnt(0)
	s_cselect_b64 s[90:91], -1, 0
	s_and_b64 s[54:55], s[84:85], s[54:55]
	s_barrier
	s_and_b64 s[54:55], s[54:55], s[90:91]
	s_andn2_b64 vcc, exec, s[54:55]
	s_mov_b64 s[54:55], -1
	s_cbranch_vccz .LBB0_699
	s_nop 0
	s_cbranch_execz .LBB0_700

.LBB0_698:
	s_and_b32 s6, s71, 3
	s_mulk_i32 s6, 0x7400
	v_add_u32_e32 v146, s6, v144
	v_add_u32_e32 v150, 0x2400, v146
	ds_read_b64_tr_b16 v[146:147], v150 offset:0
	ds_read_b64_tr_b16 v[148:149], v150 offset:0xa00
	ds_read_b64_tr_b16 v[156:157], v150 offset:64
	ds_read_b64_tr_b16 v[158:159], v150 offset:0xa40
	ds_read_b64_tr_b16 v[160:161], v150 offset:0x80
	ds_read_b64_tr_b16 v[162:163], v150 offset:0xa80
	ds_read_b64_tr_b16 v[164:165], v150 offset:0xc0
	ds_read_b64_tr_b16 v[166:167], v150 offset:0xac0
	ds_read_b64_tr_b16 v[168:169], v150 offset:0x1400
	ds_read_b64_tr_b16 v[170:171], v150 offset:0x1e00
	ds_read_b64_tr_b16 v[172:173], v150 offset:0x1440
	ds_read_b64_tr_b16 v[174:175], v150 offset:0x1e40
	ds_read_b64_tr_b16 v[176:177], v150 offset:0x1480
	ds_read_b64_tr_b16 v[178:179], v150 offset:0x1e80
	ds_read_b64_tr_b16 v[180:181], v150 offset:0x14c0
	ds_read_b64_tr_b16 v[182:183], v150 offset:0x1ec0
	s_nop 0
	s_waitcnt lgkmcnt(8)
	s_nop 0
	v_mfma_f32_32x32x16_bf16 v[82:97], v[146:149], v[126:129], v[82:97]
	v_mfma_f32_32x32x16_bf16 v[34:49], v[156:159], v[126:129], v[34:49]
	v_mfma_f32_32x32x16_bf16 v[18:33], v[160:163], v[126:129], v[18:33]
	v_mfma_f32_32x32x16_bf16 v[2:17], v[164:167], v[126:129], v[2:17]
	ds_read_b64_tr_b16 v[126:127], v150 offset:0x2800
	ds_read_b64_tr_b16 v[128:129], v150 offset:0x3200
	ds_read_b64_tr_b16 v[146:147], v150 offset:0x2840
	ds_read_b64_tr_b16 v[148:149], v150 offset:0x3240
	ds_read_b64_tr_b16 v[156:157], v150 offset:0x2880
	ds_read_b64_tr_b16 v[158:159], v150 offset:0x3280
	ds_read_b64_tr_b16 v[160:161], v150 offset:0x28c0
	ds_read_b64_tr_b16 v[162:163], v150 offset:0x32c0
	s_waitcnt lgkmcnt(8)
	s_nop 0
	v_mfma_f32_32x32x16_bf16 v[82:97], v[168:171], v[122:125], v[82:97]
	v_mfma_f32_32x32x16_bf16 v[34:49], v[172:175], v[122:125], v[34:49]
	v_mfma_f32_32x32x16_bf16 v[18:33], v[176:179], v[122:125], v[18:33]
	v_mfma_f32_32x32x16_bf16 v[2:17], v[180:183], v[122:125], v[2:17]
	ds_read_b64_tr_b16 v[122:123], v150 offset:0x3c00
	ds_read_b64_tr_b16 v[124:125], v150 offset:0x4600
	ds_read_b64_tr_b16 v[164:165], v150 offset:0x3c40
	ds_read_b64_tr_b16 v[166:167], v150 offset:0x4640
	ds_read_b64_tr_b16 v[168:169], v150 offset:0x3c80
	ds_read_b64_tr_b16 v[170:171], v150 offset:0x4680
	ds_read_b64_tr_b16 v[172:173], v150 offset:0x3cc0
	ds_read_b64_tr_b16 v[174:175], v150 offset:0x46c0
	s_waitcnt lgkmcnt(8)
	s_nop 0
	v_mfma_f32_32x32x16_bf16 v[82:97], v[126:129], v[114:117], v[82:97]
	s_waitcnt lgkmcnt(0)
	v_mfma_f32_32x32x16_bf16 v[34:49], v[146:149], v[114:117], v[34:49]
	v_mfma_f32_32x32x16_bf16 v[18:33], v[156:159], v[114:117], v[18:33]
	v_mfma_f32_32x32x16_bf16 v[2:17], v[160:163], v[114:117], v[2:17]
	v_mfma_f32_32x32x16_bf16 v[82:97], v[122:125], v[118:121], v[82:97]
	v_mfma_f32_32x32x16_bf16 v[34:49], v[164:167], v[118:121], v[34:49]
	v_mfma_f32_32x32x16_bf16 v[18:33], v[168:171], v[118:121], v[18:33]
	v_mfma_f32_32x32x16_bf16 v[2:17], v[172:175], v[118:121], v[2:17]
	s_nop 0
	s_add_i32 s6, s71, 3
	s_cmp_ge_i32 s6, s58
	s_cbranch_scc1 .LBB0_704
	s_branch .LBB0_702

.LBB0_700:
	s_and_b32 s54, s72, 3
	s_mulk_i32 s54, 0x7400
	v_add_u32_e32 v54, s54, v153
	ds_read_b128 v[50:53], v54
	ds_read_b128 v[146:149], v54 offset:32
	ds_read_b128 v[156:159], v54 offset:64
	ds_read_b128 v[160:163], v54 offset:96
	ds_read_b128 v[66:69], v54 offset:4608
	ds_read_b128 v[164:167], v54 offset:4640
	ds_read_b128 v[168:171], v54 offset:4672
	ds_read_b128 v[172:175], v54 offset:4704
	s_nop 0
	s_waitcnt lgkmcnt(0)
	v_mfma_f32_32x32x16_bf16 v[50:65], v[50:53], v[98:101], 0
	v_mfma_f32_32x32x16_bf16 v[66:81], v[66:69], v[98:101], 0
	v_mfma_f32_32x32x16_bf16 v[50:65], v[146:149], v[102:105], v[50:65]
	v_mfma_f32_32x32x16_bf16 v[66:81], v[164:167], v[102:105], v[66:81]
	v_mfma_f32_32x32x16_bf16 v[50:65], v[156:159], v[106:109], v[50:65]
	v_mfma_f32_32x32x16_bf16 v[66:81], v[168:171], v[106:109], v[66:81]
	v_mfma_f32_32x32x16_bf16 v[50:65], v[160:163], v[110:113], v[50:65]
	v_mfma_f32_32x32x16_bf16 v[66:81], v[172:175], v[110:113], v[66:81]
	s_and_b64 vcc, exec, s[6:7]
	s_cbranch_vccz .LBB0_698
.LBB0_701:
	s_nop 0
	s_add_i32 s6, s71, 3
	s_cmp_ge_i32 s6, s58
	s_cbranch_scc1 .LBB0_704

.LBB0_758:
.LBB0_759:
	s_add_i32 s26, s17, 1
	s_cmp_ge_i32 s26, s9
	s_cselect_b64 s[14:15], -1, 0
	s_cmp_ge_i32 s17, s41
	s_waitcnt vmcnt(0)
	s_cselect_b64 s[48:49], -1, 0
	s_barrier
	s_or_b64 s[48:49], s[48:49], s[14:15]
	s_mov_b64 s[14:15], -1
	s_and_b64 vcc, exec, s[48:49]
	s_cbranch_vccz .LBB0_763
	s_nop 0
	s_cbranch_execz .LBB0_764

.LBB0_762:
	s_and_b32 s6, s17, 3
	s_mulk_i32 s6, 0x5c00
	v_add_u32_e32 v0, s6, v125
	v_add_u32_e32 v0, 0x2400, v0
	ds_read_b64_tr_b16 v[126:127], v0 offset:0
	ds_read_b64_tr_b16 v[128:129], v0 offset:0x600
	ds_read_b64_tr_b16 v[130:131], v0 offset:64
	ds_read_b64_tr_b16 v[132:133], v0 offset:0x640
	ds_read_b64_tr_b16 v[134:135], v0 offset:0xc00
	ds_read_b64_tr_b16 v[136:137], v0 offset:0x1200
	ds_read_b64_tr_b16 v[138:139], v0 offset:0xc40
	ds_read_b64_tr_b16 v[140:141], v0 offset:0x1240
	ds_read_b64_tr_b16 v[142:143], v0 offset:0x1800
	ds_read_b64_tr_b16 v[144:145], v0 offset:0x1e00
	ds_read_b64_tr_b16 v[146:147], v0 offset:0x1840
	ds_read_b64_tr_b16 v[148:149], v0 offset:0x1e40
	s_nop 0
	s_waitcnt lgkmcnt(8)
	s_nop 0
	v_mfma_f32_32x32x16_bf16 v[18:33], v[126:129], v[90:93], v[18:33]
	ds_read_b64_tr_b16 v[126:127], v0 offset:0x2400
	ds_read_b64_tr_b16 v[128:129], v0 offset:0x2a00
	v_mfma_f32_32x32x16_bf16 v[2:17], v[130:133], v[90:93], v[2:17]
	ds_read_b64_tr_b16 v[90:91], v0 offset:0x2440
	ds_read_b64_tr_b16 v[92:93], v0 offset:0x2a40
	s_waitcnt lgkmcnt(8)
	s_waitcnt lgkmcnt(4)
	s_nop 0
	s_waitcnt lgkmcnt(0)
	v_mfma_f32_32x32x16_bf16 v[18:33], v[134:137], v[86:89], v[18:33]
	v_mfma_f32_32x32x16_bf16 v[2:17], v[138:141], v[86:89], v[2:17]
	v_mfma_f32_32x32x16_bf16 v[18:33], v[142:145], v[82:85], v[18:33]
	v_mfma_f32_32x32x16_bf16 v[2:17], v[146:149], v[82:85], v[2:17]
	v_mfma_f32_32x32x16_bf16 v[18:33], v[126:129], v[94:97], v[18:33]
	v_mfma_f32_32x32x16_bf16 v[2:17], v[90:93], v[94:97], v[2:17]
	s_nop 0
	s_add_i32 s6, s17, 3
	s_cmp_ge_i32 s6, s9
	s_cbranch_scc1 .LBB0_753
	s_branch .LBB0_766

.LBB0_764:
	s_and_b32 s14, s26, 3
	s_mulk_i32 s14, 0x5c00
	s_add_i32 s14, s14, 0
	v_add3_u32 v0, s14, v101, v100
	ds_read_b128 v[50:53], v0
	ds_read_b128 v[126:129], v0 offset:32
	ds_read_b128 v[130:133], v0 offset:64
	ds_read_b128 v[134:137], v0 offset:96
	ds_read_b128 v[138:141], v0 offset:4608
	ds_read_b128 v[142:145], v0 offset:4640
	ds_read_b128 v[146:149], v0 offset:4672
	ds_read_b128 v[150:153], v0 offset:4704
	s_nop 0
	s_add_i32 s14, s14, s40
	v_add_u32_e32 v0, s14, v100
	ds_read_b128 v[34:37], v0 offset:21504
	ds_read_b128 v[38:41], v0 offset:21536
	ds_read_b128 v[42:45], v0 offset:21568
	ds_read_b128 v[46:49], v0 offset:21600
	s_waitcnt lgkmcnt(0)
	v_mfma_f32_32x32x16_bf16 v[34:49], v[50:53], v[66:69], v[34:49]
	ds_read_b128 v[50:53], v0 offset:21632
	ds_read_b128 v[54:57], v0 offset:21664
	ds_read_b128 v[58:61], v0 offset:21696
	ds_read_b128 v[62:65], v0 offset:21728
	s_waitcnt lgkmcnt(0)
	v_mfma_f32_32x32x16_bf16 v[50:65], v[138:141], v[66:69], v[50:65]
	v_mfma_f32_32x32x16_bf16 v[34:49], v[126:129], v[70:73], v[34:49]
	v_mfma_f32_32x32x16_bf16 v[50:65], v[142:145], v[70:73], v[50:65]
	v_mfma_f32_32x32x16_bf16 v[34:49], v[130:133], v[74:77], v[34:49]
	v_mfma_f32_32x32x16_bf16 v[50:65], v[146:149], v[74:77], v[50:65]
	v_mfma_f32_32x32x16_bf16 v[34:49], v[134:137], v[78:81], v[34:49]
	v_mfma_f32_32x32x16_bf16 v[50:65], v[150:153], v[78:81], v[50:65]
	s_andn2_b64 vcc, exec, s[6:7]
	s_cbranch_vccz .LBB0_762
.LBB0_765:
	s_nop 0
	s_add_i32 s6, s17, 3
	s_cmp_ge_i32 s6, s9
	s_cbranch_scc1 .LBB0_753

.LBB0_775:
.LBB0_776:
	s_add_i32 s45, s44, 1
	s_cmp_ge_i32 s45, s9
	s_cselect_b64 s[16:17], -1, 0
	s_cmp_lt_i32 s45, s9
	s_cselect_b64 s[26:27], -1, 0
	s_cmp_lt_i32 s44, s41
	s_cselect_b64 s[48:49], -1, 0
	s_cmp_gt_i32 s44, -2
	s_waitcnt vmcnt(0)
	s_cselect_b64 s[52:53], -1, 0
	s_and_b64 s[26:27], s[48:49], s[26:27]
	s_barrier
	s_and_b64 s[26:27], s[26:27], s[52:53]
	s_andn2_b64 vcc, exec, s[26:27]
	s_mov_b64 s[26:27], -1
	s_cbranch_vccz .LBB0_780
	s_nop 0
	s_cbranch_execz .LBB0_781

.LBB0_779:
	s_and_b32 s6, s44, 3
	s_mulk_i32 s6, 0x5c00
	v_add_u32_e32 v116, s6, v115
	v_add_u32_e32 v121, 0x2400, v116
	ds_read_b64_tr_b16 v[116:117], v121 offset:0
	ds_read_b64_tr_b16 v[118:119], v121 offset:0x600
	ds_read_b64_tr_b16 v[122:123], v121 offset:64
	ds_read_b64_tr_b16 v[124:125], v121 offset:0x640
	ds_read_b64_tr_b16 v[126:127], v121 offset:0xc00
	ds_read_b64_tr_b16 v[128:129], v121 offset:0x1200
	ds_read_b64_tr_b16 v[130:131], v121 offset:0xc40
	ds_read_b64_tr_b16 v[132:133], v121 offset:0x1240
	ds_read_b64_tr_b16 v[134:135], v121 offset:0x1800
	ds_read_b64_tr_b16 v[136:137], v121 offset:0x1e00
	ds_read_b64_tr_b16 v[138:139], v121 offset:0x1840
	ds_read_b64_tr_b16 v[140:141], v121 offset:0x1e40
	s_nop 0
	s_waitcnt lgkmcnt(8)
	s_nop 0
	v_mfma_f32_32x32x16_bf16 v[18:33], v[116:119], v[90:93], v[18:33]
	ds_read_b64_tr_b16 v[116:117], v121 offset:0x2400
	ds_read_b64_tr_b16 v[118:119], v121 offset:0x2a00
	v_mfma_f32_32x32x16_bf16 v[2:17], v[122:125], v[90:93], v[2:17]
	ds_read_b64_tr_b16 v[90:91], v121 offset:0x2440
	ds_read_b64_tr_b16 v[92:93], v121 offset:0x2a40
	s_waitcnt lgkmcnt(8)
	s_waitcnt lgkmcnt(4)
	s_nop 0
	s_waitcnt lgkmcnt(0)
	v_mfma_f32_32x32x16_bf16 v[18:33], v[126:129], v[86:89], v[18:33]
	v_mfma_f32_32x32x16_bf16 v[2:17], v[130:133], v[86:89], v[2:17]
	v_mfma_f32_32x32x16_bf16 v[18:33], v[134:137], v[82:85], v[18:33]
	v_mfma_f32_32x32x16_bf16 v[2:17], v[138:141], v[82:85], v[2:17]
	v_mfma_f32_32x32x16_bf16 v[18:33], v[116:119], v[94:97], v[18:33]
	v_mfma_f32_32x32x16_bf16 v[2:17], v[90:93], v[94:97], v[2:17]
	s_nop 0
	s_add_i32 s6, s44, 3
	s_cmp_ge_i32 s6, s9
	s_cbranch_scc1 .LBB0_786
	s_branch .LBB0_783

.LBB0_781:
	s_and_b32 s15, s45, 3
	s_mulk_i32 s15, 0x5c00
	s_add_i32 s15, s15, 0
	v_add3_u32 v34, s15, v101, v100
	ds_read_b128 v[50:53], v34
	ds_read_b128 v[116:119], v34 offset:32
	ds_read_b128 v[122:125], v34 offset:64
	ds_read_b128 v[126:129], v34 offset:96
	ds_read_b128 v[130:133], v34 offset:4608
	ds_read_b128 v[134:137], v34 offset:4640
	ds_read_b128 v[138:141], v34 offset:4672
	ds_read_b128 v[142:145], v34 offset:4704
	s_nop 0
	s_add_i32 s15, s15, s40
	v_add_u32_e32 v62, s15, v100
	ds_read_b128 v[34:37], v62 offset:21504
	ds_read_b128 v[38:41], v62 offset:21536
	ds_read_b128 v[42:45], v62 offset:21568
	ds_read_b128 v[46:49], v62 offset:21600
	s_waitcnt lgkmcnt(0)
	v_mfma_f32_32x32x16_bf16 v[34:49], v[50:53], v[66:69], v[34:49]
	ds_read_b128 v[50:53], v62 offset:21632
	ds_read_b128 v[54:57], v62 offset:21664
	ds_read_b128 v[58:61], v62 offset:21696
	ds_read_b128 v[62:65], v62 offset:21728
	s_waitcnt lgkmcnt(0)
	v_mfma_f32_32x32x16_bf16 v[50:65], v[130:133], v[66:69], v[50:65]
	v_mfma_f32_32x32x16_bf16 v[34:49], v[116:119], v[70:73], v[34:49]
	v_mfma_f32_32x32x16_bf16 v[50:65], v[134:137], v[70:73], v[50:65]
	v_mfma_f32_32x32x16_bf16 v[34:49], v[122:125], v[74:77], v[34:49]
	v_mfma_f32_32x32x16_bf16 v[50:65], v[138:141], v[74:77], v[50:65]
	v_mfma_f32_32x32x16_bf16 v[34:49], v[126:129], v[78:81], v[34:49]
	v_mfma_f32_32x32x16_bf16 v[50:65], v[142:145], v[78:81], v[50:65]
	s_and_b64 vcc, exec, s[6:7]
	s_cbranch_vccz .LBB0_779
.LBB0_782:
	s_nop 0
	s_add_i32 s6, s44, 3
	s_cmp_ge_i32 s6, s9
	s_cbranch_scc1 .LBB0_786

.LBB0_790:
	s_setprio 0
	s_waitcnt vmcnt(0)
	s_waitcnt lgkmcnt(0)
	s_barrier
	s_mov_b64 s[4:5], exec
	v_readlane_b32 s6, v253, 42
	v_readlane_b32 s7, v253, 43
	s_and_b64 s[6:7], s[4:5], s[6:7]
	s_mov_b64 exec, s[6:7]
	s_cbranch_execz .LBB0_842
	v_readlane_b32 s7, v255, 13
	s_getreg_b32 s6, hwreg(HW_REG_XCC_ID, 0, 4)
	s_waitcnt vmcnt(0) expcnt(0) lgkmcnt(0)
	v_mov_b32_e32 v0, s7
	ds_read_b32 v3, v0
	v_readlane_b32 s7, v255, 14
	s_and_b32 s12, s6, 15
	s_waitcnt lgkmcnt(0)
	v_cmp_ne_u32_e32 vcc, 0, v3
	v_mov_b32_e32 v0, s7
	ds_read_b32 v2, v0
	s_cbranch_vccnz .LBB0_806
	s_mov_b32 s13, 1
	s_branch .LBB0_794

.LBB0_958:
	s_or_b64 exec, exec, s[4:5]
	s_mov_b32 s8, 0
	s_mov_b32 s16, 0
	s_waitcnt lgkmcnt(0)
	s_barrier
	v_readfirstlane_b32 s100, v244
	s_nop 0
	s_lshr_b32 s100, s100, 6
	s_cmp_lt_u32 s100, 4
	s_cbranch_scc1 .Lprio_1
	s_setprio 1
.Lprio_1:
	s_branch .LBB0_961
.LBB0_959:
	v_pk_add_f32 v[34:35], v[122:123], v[122:123] op_sel:[0,1] op_sel_hi:[1,0]
	s_lshl_b64 s[4:5], s[10:11], 1
	v_mov_b32_e32 v0, v34
	s_nop 1
	v_permlane32_swap_b32_e32 v34, v0
	v_add_f32_e32 v0, v34, v0
	v_div_scale_f32 v34, s[8:9], v0, v0, 1.0
	v_rcp_f32_e32 v35, v34
	s_add_u32 s4, s80, s4
	s_addc_u32 s5, s83, s5
	s_lshl_b32 s6, s22, 7
	v_fma_f32 v36, -v34, v35, 1.0
	v_fmac_f32_e32 v35, v36, v35
	v_div_scale_f32 v36, vcc, 1.0, v0, 1.0
	v_mul_f32_e32 v37, v36, v35
	s_add_u32 s4, s4, s6
	v_fma_f32 v38, -v34, v37, v36
	s_addc_u32 s5, s5, 0
	v_fmac_f32_e32 v37, v38, v35
	s_add_u32 s6, s23, s6
	v_fma_f32 v34, -v34, v37, v36
	s_addc_u32 s7, s27, 0
	v_div_fmas_f32 v34, v34, v35, v37
	v_div_fixup_f32 v36, v34, v0, 1.0
	v_mov_b64_e32 v[34:35], s[6:7]
	v_mad_i64_i32 v[34:35], s[6:7], v106, s62, v[34:35]
	v_lshlrev_b32_e32 v0, 1, v113
	v_mul_f32_e32 v42, v20, v36
	v_mul_f32_e32 v43, v21, v36
	v_lshl_add_u64 v[20:21], v[34:35], 0, v[0:1]
	v_mul_f32_e32 v40, v22, v36
	v_mul_f32_e32 v41, v23, v36
	v_mul_f32_e32 v44, v24, v36
	v_mul_f32_e32 v45, v25, v36
	global_load_dwordx4 v[22:25], v[20:21], off offset:1536
	global_load_dwordx4 v[228:231], v[20:21], off offset:1568
	global_load_dwordx4 v[232:235], v[20:21], off offset:1600
	global_load_dwordx4 v[236:239], v[20:21], off offset:1632
	v_mul_f32_e32 v18, v18, v36
	v_mul_f32_e32 v19, v19, v36
	s_nop 0
	v_permlane32_swap_b32_e32 v18, v40
	v_permlane32_swap_b32_e32 v19, v41
	v_permlane32_swap_b32_e32 v42, v44
	v_permlane32_swap_b32_e32 v43, v45
	v_lshlrev_b64 v[38:39], 11, v[106:107]
	v_lshl_add_u64 v[38:39], s[4:5], 0, v[38:39]
	v_mul_f32_e32 v6, v6, v36
	v_mul_f32_e32 v7, v7, v36
	v_mul_f32_e32 v4, v4, v36
	v_mul_f32_e32 v5, v5, v36
	s_waitcnt vmcnt(3)
	v_lshlrev_b32_e32 v34, 16, v22
	v_and_b32_e32 v35, 0xffff0000, v22
	v_mul_f32_e32 v22, 0xbfb8aa3b, v34
	v_exp_f32_e32 v22, v22
	s_nop 0
	v_add_f32_e32 v22, 1.0, v22
	v_rcp_f32_e32 v46, v22
	v_mul_f32_e32 v22, 0xbfb8aa3b, v35
	v_exp_f32_e32 v22, v22
	s_nop 0
	v_add_f32_e32 v22, 1.0, v22
	v_rcp_f32_e32 v47, v22
	v_lshlrev_b32_e32 v22, 16, v23
	v_and_b32_e32 v23, 0xffff0000, v23
	v_pk_mul_f32 v[34:35], v[46:47], v[34:35]
	s_nop 0
	v_pk_mul_f32 v[18:19], v[34:35], v[18:19]
	v_mul_f32_e32 v34, 0xbfb8aa3b, v22
	v_mul_f32_e32 v35, 0xbfb8aa3b, v23
	v_exp_f32_e32 v34, v34
	v_exp_f32_e32 v35, v35
	v_add_f32_e32 v34, 1.0, v34
	v_add_f32_e32 v35, 1.0, v35
	v_rcp_f32_e32 v34, v34
	v_rcp_f32_e32 v35, v35
	s_nop 0
	v_pk_mul_f32 v[22:23], v[34:35], v[22:23]
	s_nop 0
	v_pk_mul_f32 v[34:35], v[22:23], v[42:43]
	v_lshlrev_b32_e32 v22, 16, v24
	v_and_b32_e32 v23, 0xffff0000, v24
	v_mul_f32_e32 v24, 0xbfb8aa3b, v22
	v_exp_f32_e32 v24, v24
	s_nop 0
	v_add_f32_e32 v24, 1.0, v24
	v_rcp_f32_e32 v42, v24
	v_mul_f32_e32 v24, 0xbfb8aa3b, v23
	v_exp_f32_e32 v24, v24
	s_nop 0
	v_add_f32_e32 v24, 1.0, v24
	v_rcp_f32_e32 v43, v24
	s_nop 0
	v_pk_mul_f32 v[22:23], v[42:43], v[22:23]
	s_nop 0
	v_pk_mul_f32 v[40:41], v[22:23], v[40:41]
	v_lshlrev_b32_e32 v22, 16, v25
	v_and_b32_e32 v23, 0xffff0000, v25
	v_mul_f32_e32 v24, 0xbfb8aa3b, v22
	v_mul_f32_e32 v25, 0xbfb8aa3b, v23
	v_exp_f32_e32 v24, v24
	v_exp_f32_e32 v25, v25
	v_add_f32_e32 v24, 1.0, v24
	v_add_f32_e32 v25, 1.0, v25
	v_rcp_f32_e32 v24, v24
	v_rcp_f32_e32 v25, v25
	s_nop 0
	v_pk_mul_f32 v[22:23], v[24:25], v[22:23]
	s_nop 0
	v_pk_mul_f32 v[42:43], v[22:23], v[44:45]
	v_cvt_pk_bf16_f32 v22, v18, v19
	v_cvt_pk_bf16_f32 v23, v34, v35
	v_cvt_pk_bf16_f32 v24, v40, v41
	v_cvt_pk_bf16_f32 v25, v42, v43
	v_lshl_add_u64 v[18:19], v[38:39], 0, v[0:1]
	global_store_dwordx4 v[18:19], v[22:25], off
	v_mul_f32_e32 v34, v26, v36
	v_mul_f32_e32 v35, v27, v36
	v_mul_f32_e32 v24, v30, v36
	v_mul_f32_e32 v25, v31, v36
	v_mul_f32_e32 v26, v28, v36
	v_mul_f32_e32 v27, v29, v36
	s_nop 0
	v_mul_f32_e32 v22, v32, v36
	v_mul_f32_e32 v23, v33, v36
	v_permlane32_swap_b32_e32 v34, v24
	v_permlane32_swap_b32_e32 v35, v25
	v_permlane32_swap_b32_e32 v26, v22
	v_permlane32_swap_b32_e32 v27, v23
	s_waitcnt vmcnt(3)
	v_mov_b32_e32 v28, v228
	v_mov_b32_e32 v29, v229
	v_mov_b32_e32 v30, v230
	v_mov_b32_e32 v31, v231
	v_lshlrev_b32_e32 v32, 16, v28
	v_mul_f32_e32 v0, 0xbfb8aa3b, v32
	v_exp_f32_e32 v0, v0
	v_and_b32_e32 v33, 0xffff0000, v28
	v_lshlrev_b32_e32 v28, 16, v29
	v_and_b32_e32 v29, 0xffff0000, v29
	v_add_f32_e32 v0, 1.0, v0
	v_rcp_f32_e32 v38, v0
	v_mul_f32_e32 v0, 0xbfb8aa3b, v33
	v_exp_f32_e32 v0, v0
	s_nop 0
	v_add_f32_e32 v0, 1.0, v0
	v_rcp_f32_e32 v39, v0
	v_mul_f32_e32 v0, 0xbfb8aa3b, v28
	v_exp_f32_e32 v0, v0
	v_pk_mul_f32 v[32:33], v[38:39], v[32:33]
	s_nop 0
	v_pk_mul_f32 v[32:33], v[32:33], v[34:35]
	v_add_f32_e32 v0, 1.0, v0
	v_rcp_f32_e32 v34, v0
	v_mul_f32_e32 v0, 0xbfb8aa3b, v29
	v_exp_f32_e32 v0, v0
	s_nop 0
	v_add_f32_e32 v0, 1.0, v0
	v_rcp_f32_e32 v35, v0
	s_nop 0
	v_pk_mul_f32 v[28:29], v[34:35], v[28:29]
	s_nop 0
	v_pk_mul_f32 v[26:27], v[28:29], v[26:27]
	v_lshlrev_b32_e32 v28, 16, v30
	v_mul_f32_e32 v0, 0xbfb8aa3b, v28
	v_exp_f32_e32 v0, v0
	v_and_b32_e32 v29, 0xffff0000, v30
	v_add_f32_e32 v0, 1.0, v0
	v_rcp_f32_e32 v34, v0
	v_mul_f32_e32 v0, 0xbfb8aa3b, v29
	v_exp_f32_e32 v0, v0
	s_nop 0
	v_add_f32_e32 v0, 1.0, v0
	v_rcp_f32_e32 v35, v0
	s_nop 0
	v_pk_mul_f32 v[28:29], v[34:35], v[28:29]
	s_nop 0
	v_pk_mul_f32 v[24:25], v[28:29], v[24:25]
	v_lshlrev_b32_e32 v28, 16, v31
	v_mul_f32_e32 v0, 0xbfb8aa3b, v28
	v_exp_f32_e32 v0, v0
	v_and_b32_e32 v29, 0xffff0000, v31
	v_cvt_pk_bf16_f32 v24, v24, v25
	v_add_f32_e32 v0, 1.0, v0
	v_rcp_f32_e32 v30, v0
	v_mul_f32_e32 v0, 0xbfb8aa3b, v29
	v_exp_f32_e32 v0, v0
	s_nop 0
	v_add_f32_e32 v0, 1.0, v0
	v_rcp_f32_e32 v31, v0
	s_nop 0
	v_pk_mul_f32 v[28:29], v[30:31], v[28:29]
	s_nop 0
	v_pk_mul_f32 v[28:29], v[28:29], v[22:23]
	v_cvt_pk_bf16_f32 v22, v32, v33
	v_cvt_pk_bf16_f32 v23, v26, v27
	v_cvt_pk_bf16_f32 v25, v28, v29
	global_store_dwordx4 v[18:19], v[22:25], off offset:32
	s_nop 0
	s_nop 0
	v_mul_f32_e32 v22, v2, v36
	v_mul_f32_e32 v2, v8, v36
	v_mul_f32_e32 v23, v3, v36
	v_mul_f32_e32 v3, v9, v36
	v_permlane32_swap_b32_e32 v22, v6
	v_permlane32_swap_b32_e32 v23, v7
	v_permlane32_swap_b32_e32 v4, v2
	v_permlane32_swap_b32_e32 v5, v3
	s_waitcnt vmcnt(3)
	v_mov_b32_e32 v24, v232
	v_mov_b32_e32 v25, v233
	v_mov_b32_e32 v26, v234
	v_mov_b32_e32 v27, v235
	v_lshlrev_b32_e32 v8, 16, v24
	v_mul_f32_e32 v0, 0xbfb8aa3b, v8
	v_exp_f32_e32 v0, v0
	v_and_b32_e32 v9, 0xffff0000, v24
	v_add_f32_e32 v0, 1.0, v0
	v_rcp_f32_e32 v28, v0
	v_mul_f32_e32 v0, 0xbfb8aa3b, v9
	v_exp_f32_e32 v0, v0
	s_nop 0
	v_add_f32_e32 v0, 1.0, v0
	v_rcp_f32_e32 v29, v0
	s_nop 0
	v_pk_mul_f32 v[8:9], v[28:29], v[8:9]
	s_nop 0
	v_pk_mul_f32 v[8:9], v[8:9], v[22:23]
	v_lshlrev_b32_e32 v22, 16, v25
	v_mul_f32_e32 v0, 0xbfb8aa3b, v22
	v_exp_f32_e32 v0, v0
	v_and_b32_e32 v23, 0xffff0000, v25
	v_add_f32_e32 v0, 1.0, v0
	v_rcp_f32_e32 v24, v0
	v_mul_f32_e32 v0, 0xbfb8aa3b, v23
	v_exp_f32_e32 v0, v0
	s_nop 0
	v_add_f32_e32 v0, 1.0, v0
	v_rcp_f32_e32 v25, v0
	s_nop 0
	v_pk_mul_f32 v[22:23], v[24:25], v[22:23]
	s_nop 0
	v_pk_mul_f32 v[4:5], v[22:23], v[4:5]
	v_lshlrev_b32_e32 v22, 16, v26
	v_mul_f32_e32 v0, 0xbfb8aa3b, v22
	v_exp_f32_e32 v0, v0
	v_and_b32_e32 v23, 0xffff0000, v26
	v_add_f32_e32 v0, 1.0, v0
	v_rcp_f32_e32 v24, v0
	v_mul_f32_e32 v0, 0xbfb8aa3b, v23
	v_exp_f32_e32 v0, v0
	s_nop 0
	v_add_f32_e32 v0, 1.0, v0
	v_rcp_f32_e32 v25, v0
	s_nop 0
	v_pk_mul_f32 v[22:23], v[24:25], v[22:23]
	s_nop 0
	v_pk_mul_f32 v[6:7], v[22:23], v[6:7]
	v_lshlrev_b32_e32 v22, 16, v27
	v_mul_f32_e32 v0, 0xbfb8aa3b, v22
	v_exp_f32_e32 v0, v0
	v_and_b32_e32 v23, 0xffff0000, v27
	v_add_f32_e32 v0, 1.0, v0
	v_rcp_f32_e32 v24, v0
	v_mul_f32_e32 v0, 0xbfb8aa3b, v23
	v_exp_f32_e32 v0, v0
	s_nop 0
	v_add_f32_e32 v0, 1.0, v0
	v_rcp_f32_e32 v25, v0
	s_nop 0
	v_pk_mul_f32 v[22:23], v[24:25], v[22:23]
	s_nop 0
	v_pk_mul_f32 v[22:23], v[22:23], v[2:3]
	v_cvt_pk_bf16_f32 v2, v8, v9
	v_cvt_pk_bf16_f32 v3, v4, v5
	v_cvt_pk_bf16_f32 v4, v6, v7
	v_cvt_pk_bf16_f32 v5, v22, v23
	global_store_dwordx4 v[18:19], v[2:5], off offset:64
	s_nop 0
	v_mul_f32_e32 v22, v10, v36
	v_mul_f32_e32 v10, v12, v36
	v_mul_f32_e32 v23, v11, v36
	v_mul_f32_e32 v11, v13, v36
	v_mul_f32_e32 v8, v14, v36
	v_mul_f32_e32 v9, v15, v36
	v_mul_f32_e32 v6, v16, v36
	v_mul_f32_e32 v7, v17, v36
	s_nop 0
	v_permlane32_swap_b32_e32 v10, v6
	v_permlane32_swap_b32_e32 v11, v7
	v_permlane32_swap_b32_e32 v22, v8
	v_permlane32_swap_b32_e32 v23, v9
	s_waitcnt vmcnt(3)
	v_mov_b32_e32 v2, v236
	v_mov_b32_e32 v3, v237
	v_mov_b32_e32 v4, v238
	v_mov_b32_e32 v5, v239
	v_lshlrev_b32_e32 v12, 16, v2
	v_mul_f32_e32 v0, 0xbfb8aa3b, v12
	v_exp_f32_e32 v0, v0
	v_and_b32_e32 v13, 0xffff0000, v2
	v_lshlrev_b32_e32 v2, 16, v3
	v_and_b32_e32 v3, 0xffff0000, v3
	v_add_f32_e32 v0, 1.0, v0
	v_rcp_f32_e32 v14, v0
	v_mul_f32_e32 v0, 0xbfb8aa3b, v13
	v_exp_f32_e32 v0, v0
	s_nop 0
	v_add_f32_e32 v0, 1.0, v0
	v_rcp_f32_e32 v15, v0
	v_mul_f32_e32 v0, 0xbfb8aa3b, v2
	v_exp_f32_e32 v0, v0
	v_pk_mul_f32 v[12:13], v[14:15], v[12:13]
	s_nop 0
	v_pk_mul_f32 v[12:13], v[12:13], v[22:23]
	v_add_f32_e32 v0, 1.0, v0
	v_rcp_f32_e32 v14, v0
	v_mul_f32_e32 v0, 0xbfb8aa3b, v3
	v_exp_f32_e32 v0, v0
	s_nop 0
	v_add_f32_e32 v0, 1.0, v0
	v_rcp_f32_e32 v15, v0
	s_nop 0
	v_pk_mul_f32 v[2:3], v[14:15], v[2:3]
	s_nop 0
	v_pk_mul_f32 v[10:11], v[2:3], v[10:11]
	v_lshlrev_b32_e32 v2, 16, v4
	v_mul_f32_e32 v0, 0xbfb8aa3b, v2
	v_exp_f32_e32 v0, v0
	v_and_b32_e32 v3, 0xffff0000, v4
	v_add_f32_e32 v0, 1.0, v0
	v_rcp_f32_e32 v14, v0
	v_mul_f32_e32 v0, 0xbfb8aa3b, v3
	v_exp_f32_e32 v0, v0
	s_nop 0
	v_add_f32_e32 v0, 1.0, v0
	v_rcp_f32_e32 v15, v0
	s_nop 0
	v_pk_mul_f32 v[2:3], v[14:15], v[2:3]
	s_nop 0
	v_pk_mul_f32 v[8:9], v[2:3], v[8:9]
	v_lshlrev_b32_e32 v2, 16, v5
	v_mul_f32_e32 v0, 0xbfb8aa3b, v2
	v_exp_f32_e32 v0, v0
	v_and_b32_e32 v3, 0xffff0000, v5
	v_add_f32_e32 v0, 1.0, v0
	v_rcp_f32_e32 v4, v0
	v_mul_f32_e32 v0, 0xbfb8aa3b, v3
	v_exp_f32_e32 v0, v0
	s_nop 0
	v_add_f32_e32 v0, 1.0, v0
	v_rcp_f32_e32 v5, v0
	s_nop 0
	v_pk_mul_f32 v[2:3], v[4:5], v[2:3]
	s_nop 0
	v_pk_mul_f32 v[6:7], v[2:3], v[6:7]
	v_cvt_pk_bf16_f32 v2, v12, v13
	v_cvt_pk_bf16_f32 v3, v10, v11
	v_cvt_pk_bf16_f32 v4, v8, v9
	v_cvt_pk_bf16_f32 v5, v6, v7
	global_store_dwordx4 v[18:19], v[2:5], off offset:96

.LBB0_1023:
.LBB0_1024:
	s_add_i32 s40, s15, 1
	s_cmp_ge_i32 s40, s37
	s_cselect_b64 s[12:13], -1, 0
	s_cmp_ge_i32 s15, s38
	s_waitcnt vmcnt(0)
	s_cselect_b64 s[44:45], -1, 0
	s_barrier
	s_or_b64 s[44:45], s[44:45], s[12:13]
	s_mov_b64 s[12:13], -1
	s_and_b64 vcc, exec, s[44:45]
	s_cbranch_vccz .LBB0_1028
	s_nop 0
	s_cbranch_execz .LBB0_1029

.LBB0_1027:
	s_and_b32 s10, s15, 3
	s_mulk_i32 s10, 0x6400
	v_add_u32_e32 v138, s10, v107
	v_add_u32_e32 v162, 0x3400, v138
	ds_read_b64_tr_b16 v[138:139], v162 offset:0
	ds_read_b64_tr_b16 v[140:141], v162 offset:0x600
	ds_read_b64_tr_b16 v[142:143], v162 offset:64
	ds_read_b64_tr_b16 v[144:145], v162 offset:0x640
	ds_read_b64_tr_b16 v[146:147], v162 offset:0xc00
	ds_read_b64_tr_b16 v[148:149], v162 offset:0x1200
	ds_read_b64_tr_b16 v[150:151], v162 offset:0xc40
	ds_read_b64_tr_b16 v[152:153], v162 offset:0x1240
	ds_read_b64_tr_b16 v[154:155], v162 offset:0x1800
	ds_read_b64_tr_b16 v[156:157], v162 offset:0x1e00
	ds_read_b64_tr_b16 v[158:159], v162 offset:0x1840
	ds_read_b64_tr_b16 v[160:161], v162 offset:0x1e40
	s_nop 0
	s_waitcnt lgkmcnt(8)
	s_nop 0
	v_mfma_f32_32x32x16_bf16 v[18:33], v[138:141], v[98:101], v[18:33]
	ds_read_b64_tr_b16 v[138:139], v162 offset:0x2400
	ds_read_b64_tr_b16 v[140:141], v162 offset:0x2a00
	v_mfma_f32_32x32x16_bf16 v[2:17], v[142:145], v[98:101], v[2:17]
	ds_read_b64_tr_b16 v[98:99], v162 offset:0x2440
	ds_read_b64_tr_b16 v[100:101], v162 offset:0x2a40
	s_waitcnt lgkmcnt(8)
	s_waitcnt lgkmcnt(4)
	s_nop 0
	s_waitcnt lgkmcnt(0)
	v_mfma_f32_32x32x16_bf16 v[18:33], v[146:149], v[94:97], v[18:33]
	v_mfma_f32_32x32x16_bf16 v[2:17], v[150:153], v[94:97], v[2:17]
	v_mfma_f32_32x32x16_bf16 v[18:33], v[154:157], v[90:93], v[18:33]
	v_mfma_f32_32x32x16_bf16 v[2:17], v[158:161], v[90:93], v[2:17]
	v_mfma_f32_32x32x16_bf16 v[18:33], v[138:141], v[102:105], v[18:33]
	v_mfma_f32_32x32x16_bf16 v[2:17], v[98:101], v[102:105], v[2:17]
	s_nop 0
	s_add_i32 s10, s15, 3
	s_cmp_ge_i32 s10, s37
	s_cbranch_scc1 .LBB0_1018
	s_branch .LBB0_1031

.LBB0_1029:
	s_and_b32 s12, s40, 3
	s_mulk_i32 s12, 0x6400
	v_add_u32_e32 v38, s12, v132
	ds_read_b128 v[34:37], v38
	ds_read_b128 v[138:141], v38 offset:32
	ds_read_b128 v[142:145], v38 offset:64
	ds_read_b128 v[146:149], v38 offset:96
	ds_read_b128 v[150:153], v38 offset:128
	ds_read_b128 v[154:157], v38 offset:160
	ds_read_b128 v[50:53], v38 offset:6656
	ds_read_b128 v[158:161], v38 offset:6688
	ds_read_b128 v[162:165], v38 offset:6720
	ds_read_b128 v[166:169], v38 offset:6752
	ds_read_b128 v[170:173], v38 offset:6784
	ds_read_b128 v[174:177], v38 offset:6816
	s_nop 0
	s_waitcnt lgkmcnt(0)
	v_mfma_f32_32x32x16_bf16 v[34:49], v[34:37], v[66:69], 0
	v_mfma_f32_32x32x16_bf16 v[50:65], v[50:53], v[66:69], 0
	v_mfma_f32_32x32x16_bf16 v[34:49], v[138:141], v[70:73], v[34:49]
	v_mfma_f32_32x32x16_bf16 v[50:65], v[158:161], v[70:73], v[50:65]
	v_mfma_f32_32x32x16_bf16 v[34:49], v[142:145], v[74:77], v[34:49]
	v_mfma_f32_32x32x16_bf16 v[50:65], v[162:165], v[74:77], v[50:65]
	v_mfma_f32_32x32x16_bf16 v[34:49], v[146:149], v[78:81], v[34:49]
	v_mfma_f32_32x32x16_bf16 v[50:65], v[166:169], v[78:81], v[50:65]
	v_mfma_f32_32x32x16_bf16 v[34:49], v[150:153], v[82:85], v[34:49]
	v_mfma_f32_32x32x16_bf16 v[50:65], v[170:173], v[82:85], v[50:65]
	v_mfma_f32_32x32x16_bf16 v[34:49], v[154:157], v[86:89], v[34:49]
	v_mfma_f32_32x32x16_bf16 v[50:65], v[174:177], v[86:89], v[50:65]
	s_andn2_b64 vcc, exec, s[10:11]
	s_cbranch_vccz .LBB0_1027
.LBB0_1030:
	s_nop 0
	s_add_i32 s10, s15, 3
	s_cmp_ge_i32 s10, s37
	s_cbranch_scc1 .LBB0_1018

.LBB0_1040:
.LBB0_1041:
	s_add_i32 s40, s39, 1
	s_cmp_ge_i32 s40, s37
	s_cselect_b64 s[12:13], -1, 0
	s_cmp_lt_i32 s40, s37
	s_cselect_b64 s[14:15], -1, 0
	s_cmp_lt_i32 s39, s38
	s_cselect_b64 s[44:45], -1, 0
	s_cmp_gt_i32 s39, -2
	s_waitcnt vmcnt(0)
	s_cselect_b64 s[48:49], -1, 0
	s_and_b64 s[14:15], s[44:45], s[14:15]
	s_barrier
	s_and_b64 s[14:15], s[14:15], s[48:49]
	s_andn2_b64 vcc, exec, s[14:15]
	s_mov_b64 s[14:15], -1
	s_cbranch_vccz .LBB0_1045
	s_nop 0
	s_cbranch_execz .LBB0_1046

.LBB0_1044:
	s_and_b32 s6, s39, 3
	s_mulk_i32 s6, 0x6400
	v_add_u32_e32 v124, s6, v117
	v_add_u32_e32 v133, 0x3400, v124
	ds_read_b64_tr_b16 v[124:125], v133 offset:0
	ds_read_b64_tr_b16 v[126:127], v133 offset:0x600
	ds_read_b64_tr_b16 v[128:129], v133 offset:64
	ds_read_b64_tr_b16 v[130:131], v133 offset:0x640
	ds_read_b64_tr_b16 v[136:137], v133 offset:0xc00
	ds_read_b64_tr_b16 v[138:139], v133 offset:0x1200
	ds_read_b64_tr_b16 v[140:141], v133 offset:0xc40
	ds_read_b64_tr_b16 v[142:143], v133 offset:0x1240
	ds_read_b64_tr_b16 v[144:145], v133 offset:0x1800
	ds_read_b64_tr_b16 v[146:147], v133 offset:0x1e00
	ds_read_b64_tr_b16 v[148:149], v133 offset:0x1840
	ds_read_b64_tr_b16 v[150:151], v133 offset:0x1e40
	s_nop 0
	s_waitcnt lgkmcnt(8)
	s_nop 0
	v_mfma_f32_32x32x16_bf16 v[18:33], v[124:127], v[98:101], v[18:33]
	ds_read_b64_tr_b16 v[124:125], v133 offset:0x2400
	ds_read_b64_tr_b16 v[126:127], v133 offset:0x2a00
	v_mfma_f32_32x32x16_bf16 v[2:17], v[128:131], v[98:101], v[2:17]
	ds_read_b64_tr_b16 v[98:99], v133 offset:0x2440
	ds_read_b64_tr_b16 v[100:101], v133 offset:0x2a40
	s_waitcnt lgkmcnt(8)
	s_waitcnt lgkmcnt(4)
	s_nop 0
	s_waitcnt lgkmcnt(0)
	v_mfma_f32_32x32x16_bf16 v[18:33], v[136:139], v[94:97], v[18:33]
	v_mfma_f32_32x32x16_bf16 v[2:17], v[140:143], v[94:97], v[2:17]
	v_mfma_f32_32x32x16_bf16 v[18:33], v[144:147], v[90:93], v[18:33]
	v_mfma_f32_32x32x16_bf16 v[2:17], v[148:151], v[90:93], v[2:17]
	v_mfma_f32_32x32x16_bf16 v[18:33], v[124:127], v[102:105], v[18:33]
	v_mfma_f32_32x32x16_bf16 v[2:17], v[98:101], v[102:105], v[2:17]
	s_nop 0
	s_add_i32 s6, s39, 3
	s_cmp_ge_i32 s6, s37
	s_cbranch_scc1 .LBB0_1050
	s_branch .LBB0_1048

.LBB0_1046:
	s_and_b32 s14, s40, 3
	s_mulk_i32 s14, 0x6400
	v_add_u32_e32 v38, s14, v132
	ds_read_b128 v[34:37], v38
	ds_read_b128 v[124:127], v38 offset:32
	ds_read_b128 v[128:131], v38 offset:64
	ds_read_b128 v[136:139], v38 offset:96
	ds_read_b128 v[140:143], v38 offset:128
	ds_read_b128 v[144:147], v38 offset:160
	ds_read_b128 v[50:53], v38 offset:6656
	ds_read_b128 v[148:151], v38 offset:6688
	ds_read_b128 v[152:155], v38 offset:6720
	ds_read_b128 v[156:159], v38 offset:6752
	ds_read_b128 v[160:163], v38 offset:6784
	ds_read_b128 v[164:167], v38 offset:6816
	s_nop 0
	s_waitcnt lgkmcnt(0)
	v_mfma_f32_32x32x16_bf16 v[34:49], v[34:37], v[66:69], 0
	v_mfma_f32_32x32x16_bf16 v[50:65], v[50:53], v[66:69], 0
	v_mfma_f32_32x32x16_bf16 v[34:49], v[124:127], v[70:73], v[34:49]
	v_mfma_f32_32x32x16_bf16 v[50:65], v[148:151], v[70:73], v[50:65]
	v_mfma_f32_32x32x16_bf16 v[34:49], v[128:131], v[74:77], v[34:49]
	v_mfma_f32_32x32x16_bf16 v[50:65], v[152:155], v[74:77], v[50:65]
	v_mfma_f32_32x32x16_bf16 v[34:49], v[136:139], v[78:81], v[34:49]
	v_mfma_f32_32x32x16_bf16 v[50:65], v[156:159], v[78:81], v[50:65]
	v_mfma_f32_32x32x16_bf16 v[34:49], v[140:143], v[82:85], v[34:49]
	v_mfma_f32_32x32x16_bf16 v[50:65], v[160:163], v[82:85], v[50:65]
	v_mfma_f32_32x32x16_bf16 v[34:49], v[144:147], v[86:89], v[34:49]
	v_mfma_f32_32x32x16_bf16 v[50:65], v[164:167], v[86:89], v[50:65]
	s_and_b64 vcc, exec, s[6:7]
	s_cbranch_vccz .LBB0_1044
.LBB0_1047:
	s_nop 0
	s_add_i32 s6, s39, 3
	s_cmp_ge_i32 s6, s37
	s_cbranch_scc1 .LBB0_1050
